# v113 + own-phase YB stores write-through (sc1)
# speedup vs baseline: 1.0274x; 1.0011x over previous
.LBB0_925:
	s_waitcnt vmcnt(2)
	v_cndmask_b32_e32 v64, 0, v129, vcc
	v_cndmask_b32_e64 v65, v128, 0, s[86:87]
	v_cndmask_b32_e64 v66, 0, v130, s[38:39]
	v_add_f32_e32 v64, v65, v64
	v_add_f32_e32 v64, v66, v64
	s_waitcnt lgkmcnt(0)
	v_add_f32_e32 v65, v159, v161
	v_add_f32_e32 v64, v64, v65
	v_div_scale_f32 v65, s[38:39], v64, v64, 1.0
	v_rcp_f32_e32 v66, v65
	s_add_u32 s38, s58, s96
	s_addc_u32 s39, s59, 0
	s_add_i32 s86, s62, 1
	v_fma_f32 v67, -v65, v66, 1.0
	v_fmac_f32_e32 v66, v67, v66
	v_div_scale_f32 v67, vcc, 1.0, v64, 1.0
	s_waitcnt vmcnt(0)
	v_mul_f32_e32 v68, v67, v66
	v_fma_f32 v69, -v65, v68, v67
	v_fmac_f32_e32 v68, v69, v66
	v_fma_f32 v65, -v65, v68, v67
	v_div_fmas_f32 v65, v65, v66, v68
	v_div_fixup_f32 v68, v65, v64, 1.0
	v_mul_f32_e32 v48, v68, v48
	v_mul_f32_e32 v49, v68, v49
	v_cvt_pk_bf16_f32 v48, v48, v49
	v_mul_f32_e32 v49, v68, v50
	v_mul_f32_e32 v50, v68, v51
	v_cvt_pk_bf16_f32 v49, v49, v50
	ds_write_b64 v158, v[48:49]
	v_mul_f32_e32 v48, v68, v52
	v_mul_f32_e32 v49, v68, v53
	v_cvt_pk_bf16_f32 v48, v48, v49
	v_mul_f32_e32 v49, v68, v54
	v_mul_f32_e32 v50, v68, v55
	v_cvt_pk_bf16_f32 v49, v49, v50
	ds_write_b64 v158, v[48:49] offset:16
	v_mul_f32_e32 v48, v68, v56
	v_mul_f32_e32 v49, v68, v57
	v_cvt_pk_bf16_f32 v48, v48, v49
	v_mul_f32_e32 v49, v68, v58
	v_mul_f32_e32 v50, v68, v59
	v_cvt_pk_bf16_f32 v49, v49, v50
	ds_write_b64 v158, v[48:49] offset:32
	v_mul_f32_e32 v48, v68, v60
	v_mul_f32_e32 v49, v68, v61
	v_cvt_pk_bf16_f32 v48, v48, v49
	v_mul_f32_e32 v49, v68, v62
	v_mul_f32_e32 v50, v68, v63
	v_cvt_pk_bf16_f32 v49, v49, v50
	ds_write_b64 v158, v[48:49] offset:48
	ds_read_b128 v[48:51], v157
	ds_read_b128 v[52:55], v160
	v_mov_b32_e32 v65, s39
	v_or_b32_e32 v64, s38, v132
	v_lshlrev_b64 v[64:65], 11, v[64:65]
	v_mov_b32_e32 v67, s39
	v_or_b32_e32 v66, s38, v134
	v_lshlrev_b64 v[56:57], 11, v[66:67]
	v_lshl_add_u64 v[58:59], v[142:143], 0, v[64:65]
	v_lshl_add_u64 v[56:57], v[142:143], 0, v[56:57]
	s_waitcnt lgkmcnt(0)
	global_store_dwordx4 v[58:59], v[52:55], off sc1
	global_store_dwordx4 v[56:57], v[48:51], off sc1
	v_mul_f32_e32 v32, v68, v32
	v_mul_f32_e32 v33, v68, v33
	v_cvt_pk_bf16_f32 v32, v32, v33
	v_mul_f32_e32 v33, v68, v34
	v_mul_f32_e32 v34, v68, v35
	v_cvt_pk_bf16_f32 v33, v33, v34
	ds_write_b64 v158, v[32:33]
	v_mul_f32_e32 v32, v68, v36
	v_mul_f32_e32 v33, v68, v37
	v_cvt_pk_bf16_f32 v32, v32, v33
	v_mul_f32_e32 v33, v68, v38
	v_mul_f32_e32 v34, v68, v39
	v_cvt_pk_bf16_f32 v33, v33, v34
	ds_write_b64 v158, v[32:33] offset:16
	v_mul_f32_e32 v32, v68, v40
	v_mul_f32_e32 v33, v68, v41
	v_cvt_pk_bf16_f32 v32, v32, v33
	v_mul_f32_e32 v33, v68, v42
	v_mul_f32_e32 v34, v68, v43
	v_cvt_pk_bf16_f32 v33, v33, v34
	ds_write_b64 v158, v[32:33] offset:32
	v_mul_f32_e32 v32, v68, v44
	v_mul_f32_e32 v33, v68, v45
	v_cvt_pk_bf16_f32 v32, v32, v33
	v_mul_f32_e32 v33, v68, v46
	v_mul_f32_e32 v34, v68, v47
	v_cvt_pk_bf16_f32 v33, v33, v34
	ds_write_b64 v158, v[32:33] offset:48
	ds_read_b128 v[32:35], v160
	ds_read_b128 v[36:39], v157
	s_waitcnt lgkmcnt(1)
	global_store_dwordx4 v[58:59], v[32:35], off offset:64 sc1
	s_waitcnt lgkmcnt(0)
	global_store_dwordx4 v[56:57], v[36:39], off offset:64 sc1
	v_mul_f32_e32 v16, v68, v16
	v_mul_f32_e32 v17, v68, v17
	v_cvt_pk_bf16_f32 v16, v16, v17
	v_mul_f32_e32 v17, v68, v18
	v_mul_f32_e32 v18, v68, v19
	v_cvt_pk_bf16_f32 v17, v17, v18
	ds_write_b64 v158, v[16:17]
	v_mul_f32_e32 v16, v68, v20
	v_mul_f32_e32 v17, v68, v21
	v_cvt_pk_bf16_f32 v16, v16, v17
	v_mul_f32_e32 v17, v68, v22
	v_mul_f32_e32 v18, v68, v23
	v_cvt_pk_bf16_f32 v17, v17, v18
	ds_write_b64 v158, v[16:17] offset:16
	v_mul_f32_e32 v16, v68, v24
	v_mul_f32_e32 v17, v68, v25
	v_cvt_pk_bf16_f32 v16, v16, v17
	v_mul_f32_e32 v17, v68, v26
	v_mul_f32_e32 v18, v68, v27
	v_cvt_pk_bf16_f32 v17, v17, v18
	ds_write_b64 v158, v[16:17] offset:32
	v_mul_f32_e32 v16, v68, v28
	v_mul_f32_e32 v17, v68, v29
	v_cvt_pk_bf16_f32 v16, v16, v17
	v_mul_f32_e32 v17, v68, v30
	v_mul_f32_e32 v18, v68, v31
	v_cvt_pk_bf16_f32 v17, v17, v18
	ds_write_b64 v158, v[16:17] offset:48
	ds_read_b128 v[16:19], v160
	ds_read_b128 v[20:23], v157
	s_waitcnt lgkmcnt(1)
	global_store_dwordx4 v[58:59], v[16:19], off offset:128 sc1
	s_waitcnt lgkmcnt(0)
	global_store_dwordx4 v[56:57], v[20:23], off offset:128 sc1
	v_mul_f32_e32 v0, v68, v0
	v_mul_f32_e32 v1, v68, v1
	v_cvt_pk_bf16_f32 v0, v0, v1
	v_mul_f32_e32 v1, v68, v2
	v_mul_f32_e32 v2, v68, v3
	v_cvt_pk_bf16_f32 v1, v1, v2
	ds_write_b64 v158, v[0:1]
	v_mul_f32_e32 v0, v68, v4
	v_mul_f32_e32 v1, v68, v5
	v_cvt_pk_bf16_f32 v0, v0, v1
	v_mul_f32_e32 v1, v68, v6
	v_mul_f32_e32 v2, v68, v7
	v_cvt_pk_bf16_f32 v1, v1, v2
	ds_write_b64 v158, v[0:1] offset:16
	v_mul_f32_e32 v0, v68, v8
	v_mul_f32_e32 v1, v68, v9
	v_cvt_pk_bf16_f32 v0, v0, v1
	v_mul_f32_e32 v1, v68, v10
	v_mul_f32_e32 v2, v68, v11
	v_cvt_pk_bf16_f32 v1, v1, v2
	ds_write_b64 v158, v[0:1] offset:32
	v_mul_f32_e32 v0, v68, v12
	v_mul_f32_e32 v1, v68, v13
	v_cvt_pk_bf16_f32 v0, v0, v1
	v_mul_f32_e32 v1, v68, v14
	v_mul_f32_e32 v2, v68, v15
	v_cvt_pk_bf16_f32 v1, v1, v2
	ds_write_b64 v158, v[0:1] offset:48
	ds_read_b128 v[0:3], v160
	ds_read_b128 v[4:7], v157
	s_cmp_lg_u32 s62, 3
	s_cselect_b32 s38, s86, 3
	s_add_i32 s62, s38, s44
	s_ashr_i32 s38, s62, 8
	s_lshl_b32 s87, s62, 8
	s_ashr_i32 s39, s38, 31
	s_and_b32 s87, s87, 0x1f00
	s_waitcnt lgkmcnt(1)
	global_store_dwordx4 v[58:59], v[0:3], off offset:192 sc1
	s_waitcnt lgkmcnt(0)
	global_store_dwordx4 v[56:57], v[4:7], off offset:192 sc1
	s_lshl_b64 s[38:39], s[38:39], 13
	s_add_i32 s87, s87, s64
	v_mbcnt_lo_u32_b32 v2, -1, 0
	v_mbcnt_hi_u32_b32 v2, -1, v2
	s_add_u32 s38, s38, s87
	v_ashrrev_i32_e32 v0, 2, v2
	v_ashrrev_i32_e32 v1, 31, v0
	s_addc_u32 s39, s39, 0
	v_lshl_add_u64 v[0:1], s[38:39], 0, v[0:1]
	v_lshlrev_b64 v[0:1], 11, v[0:1]
	s_lshl_b32 s38, s62, 3
	v_lshl_add_u64 v[0:1], s[56:57], 0, v[0:1]
	s_and_b32 s62, s38, 0x700
	v_lshlrev_b32_e32 v2, 4, v2
	v_lshl_add_u64 v[0:1], v[0:1], 0, s[62:63]
	v_and_b32_e32 v138, 48, v2
	v_lshl_add_u64 v[16:17], v[0:1], 0, v[138:139]
	v_add_co_u32_e32 v24, vcc, 0x8000, v16
	s_cmp_lg_u32 s86, 4
	s_nop 0
	v_addc_co_u32_e32 v25, vcc, 0, v17, vcc
	global_load_dwordx4 v[0:3], v[16:17], off
	global_load_dwordx4 v[4:7], v[16:17], off offset:64
	global_load_dwordx4 v[20:23], v[24:25], off
	global_load_dwordx4 v[12:15], v[24:25], off offset:64
	global_load_dwordx4 v[8:11], v[16:17], off offset:128
	s_nop 0
	global_load_dwordx4 v[16:19], v[16:17], off offset:192
	s_nop 0
	global_load_dwordx4 v[28:31], v[24:25], off offset:128
	s_nop 0
	global_load_dwordx4 v[24:27], v[24:25], off offset:192
	s_mov_b32 s62, s86
	s_cbranch_scc0 .LBB0_938
